# v091 + P2 head loop: rstd vector loaded from LDS once before the loop (v158-v165) instead of 8 ds_read_b128 per head; dependent lgkmcnt waits removed
# baseline (speedup 1.0000x reference)
.LBB0_395:
	s_or_b64 exec, exec, s[46:47]
	v_lshrrev_b32_e32 v3, 2, v18
	v_and_b32_e32 v3, 16, v3
	v_lshrrev_b32_e32 v4, 5, v18
	v_and_or_b32 v3, v4, 12, v3
	v_and_or_b32 v8, v0, s51, v3
	v_mul_lo_u32 v51, v8, s60
	v_add_u32_e32 v8, 0x200, v18
	v_ashrrev_i32_e32 v22, 4, v8
	v_and_or_b32 v8, v22, s51, v3
	v_mul_lo_u32 v52, v8, s60
	v_add_u32_e32 v8, 0x400, v18
	v_lshlrev_b32_e32 v6, 3, v19
	v_lshlrev_b32_e32 v50, 4, v19
	v_ashrrev_i32_e32 v19, 4, v8
	v_and_or_b32 v8, v19, s51, v3
	v_mul_lo_u32 v53, v8, s60
	v_add_u32_e32 v8, 0x600, v18
	v_ashrrev_i32_e32 v2, 7, v18
	v_ashrrev_i32_e32 v14, 4, v8
	s_and_b32 s33, s10, 1
	v_lshlrev_b32_e32 v5, 5, v2
	v_and_or_b32 v3, v14, s51, v3
	v_lshlrev_b32_e32 v2, 12, v2
	v_mul_lo_u32 v54, v3, s60
	v_lshlrev_b32_e32 v3, 7, v1
	v_lshl_add_u32 v2, s33, 16, v2
	s_lshl_b32 s8, s33, 9
	v_or3_b32 v56, v2, v3, v6
	v_add_u32_e32 v2, s8, v5
	s_lshr_b32 s46, s10, 1
	v_or_b32_e32 v2, v2, v1
	s_lshl_b32 s10, s46, 7
	v_ashrrev_i32_e32 v3, 31, v2
	v_lshl_add_u64 v[8:9], v[2:3], 2, s[36:37]
	v_add_u32_e32 v2, s10, v5
	v_and_b32_e32 v7, 64, v18
	v_or_b32_e32 v2, v2, v1
	v_lshl_add_u32 v48, v1, 5, 0
	v_lshlrev_b32_e32 v49, 4, v1
	v_and_b32_e32 v4, 0x4f, v18
	v_or3_b32 v1, v7, s8, v6
	v_ashrrev_i32_e32 v3, 31, v2
	v_mul_u32_u24_e32 v55, 0x110, v4
	v_or_b32_e32 v4, 16, v2
	v_lshl_or_b32 v6, v1, 1, v115
	v_mov_b32_e32 v7, v61
	v_lshlrev_b64 v[2:3], 12, v[2:3]
	v_lshl_add_u64 v[12:13], v[2:3], 0, v[6:7]
	v_add_u32_e32 v2, s8, v14
	v_ashrrev_i32_e32 v3, 31, v2
	v_lshl_add_u64 v[14:15], v[2:3], 2, s[24:25]
	v_lshlrev_b64 v[2:3], 15, v[2:3]
	v_or_b32_e32 v2, s64, v2
	v_lshl_add_u64 v[2:3], v[2:3], 0, v[60:61]
	v_lshl_add_u64 v[16:17], v[2:3], 0, s[42:43]
	v_add_u32_e32 v2, s8, v19
	v_ashrrev_i32_e32 v3, 31, v2
	v_lshl_add_u64 v[18:19], v[2:3], 2, s[24:25]
	v_lshlrev_b64 v[2:3], 15, v[2:3]
	v_or_b32_e32 v2, s64, v2
	v_lshl_add_u64 v[2:3], v[2:3], 0, v[60:61]
	v_lshl_add_u64 v[20:21], v[2:3], 0, s[42:43]
	v_add_u32_e32 v2, s8, v22
	v_add_u32_e32 v0, s8, v0
	v_ashrrev_i32_e32 v3, 31, v2
	v_ashrrev_i32_e32 v1, 31, v0
	v_lshl_add_u64 v[22:23], v[2:3], 2, s[24:25]
	v_lshlrev_b64 v[2:3], 15, v[2:3]
	v_lshl_add_u64 v[26:27], v[0:1], 2, s[24:25]
	v_lshlrev_b64 v[0:1], 15, v[0:1]
	v_ashrrev_i32_e32 v5, 31, v4
	v_or_b32_e32 v2, s64, v2
	v_or_b32_e32 v0, s64, v0
	v_lshlrev_b64 v[4:5], 12, v[4:5]
	v_lshl_add_u64 v[2:3], v[2:3], 0, v[60:61]
	v_lshl_add_u64 v[0:1], v[0:1], 0, v[60:61]
	s_lshl_b32 s47, s33, 2
	v_lshl_add_u64 v[10:11], v[4:5], 0, v[6:7]
	v_lshl_add_u64 v[24:25], v[2:3], 0, s[42:43]
	v_lshl_add_u64 v[28:29], v[0:1], 0, s[42:43]
	s_mov_b32 s64, 0
	s_mov_b64 s[8:9], 0
	s_waitcnt lgkmcnt(0)
	s_barrier
	ds_read_b128 v[158:161], v48 offset:4096
	ds_read_b128 v[162:165], v48 offset:4112
.LBB0_396:
	v_lshl_add_u64 v[30:31], s[56:57], 0, v[28:29]
	v_lshl_add_u64 v[32:33], v[26:27], 0, s[8:9]
	v_lshl_add_u64 v[36:37], v[22:23], 0, s[8:9]
	v_lshl_add_u64 v[38:39], s[56:57], 0, v[24:25]
	v_lshl_add_u64 v[46:47], s[56:57], 0, v[20:21]
	v_lshl_add_u64 v[58:59], s[56:57], 0, v[16:17]
	global_load_dword v60, v[32:33], off
	s_nop 0
	global_load_dwordx4 v[30:33], v[30:31], off
	s_nop 0
	global_load_dwordx4 v[62:65], v[38:39], off
	global_load_dwordx4 v[66:69], v[46:47], off
	global_load_dwordx4 v[70:73], v[58:59], off
	s_nop 0
	global_load_dword v36, v[36:37], off
	v_lshl_add_u64 v[44:45], v[18:19], 0, s[8:9]
	v_lshl_add_u64 v[74:75], v[14:15], 0, s[8:9]
	global_load_dword v38, v[44:45], off
	s_nop 0
	global_load_dword v44, v[74:75], off
	s_bitcmp1_b32 s47, 0
	s_cselect_b32 s65, 0x8800, 0
	s_add_i32 s65, s65, 0
	v_add_u32_e32 v37, s65, v49
	v_add_u32_e32 v39, v37, v51
	v_add_u32_e32 v42, s64, v56
	v_ashrrev_i32_e32 v43, 31, v42
	v_lshl_add_u64 v[74:75], v[42:43], 1, s[38:39]
	v_add_u32_e32 v43, v37, v52
	v_add_u32_e32 v45, v37, v53
	v_add_u32_e32 v37, v37, v54
	v_add_u32_e32 v46, 0x800, v42
	v_ashrrev_i32_e32 v47, 31, v46
	v_lshl_add_u64 v[46:47], v[46:47], 1, s[38:39]
	v_add3_u32 v57, s65, v50, v55
	v_add_u32_e32 v58, 32, v42
	v_add_u32_e32 v94, 0x820, v42
	v_ashrrev_i32_e32 v59, 31, v58
	v_add_u32_e32 v100, 64, v42
	v_add_u32_e32 v102, 0x840, v42
	v_add_u32_e32 v104, 0x60, v42
	v_add_u32_e32 v106, 0x860, v42
	v_ashrrev_i32_e32 v95, 31, v94
	v_ashrrev_i32_e32 v101, 31, v100
	v_ashrrev_i32_e32 v103, 31, v102
	v_lshl_add_u64 v[98:99], s[56:57], 0, v[12:13]
	v_add_co_u32_e32 v110, vcc, s61, v98
	v_ashrrev_i32_e32 v105, 31, v104
	s_nop 0
	v_addc_co_u32_e32 v111, vcc, 0, v99, vcc
	v_lshl_add_u64 v[120:121], v[104:105], 1, s[38:39]
	v_ashrrev_i32_e32 v107, 31, v106
	v_lshl_add_u64 v[40:41], v[8:9], 0, s[8:9]
	v_lshl_add_u64 v[128:129], v[106:107], 1, s[38:39]
	v_lshl_add_u64 v[34:35], s[56:57], 0, v[10:11]
	v_add_co_u32_e32 v236, vcc, s61, v34
	global_load_dwordx4 v[176:179], v[74:75], off
	global_load_dwordx4 v[180:183], v[46:47], off
	v_addc_co_u32_e32 v237, vcc, 0, v35, vcc
	v_lshl_add_u64 v[228:229], v[58:59], 1, s[38:39]
	v_lshl_add_u64 v[230:231], v[94:95], 1, s[38:39]
	v_lshl_add_u64 v[232:233], v[100:101], 1, s[38:39]
	v_lshl_add_u64 v[234:235], v[102:103], 1, s[38:39]
	global_load_dwordx4 v[184:187], v[228:229], off
	global_load_dwordx4 v[188:191], v[230:231], off
	global_load_dwordx4 v[192:195], v[232:233], off
	global_load_dwordx4 v[196:199], v[234:235], off
	global_load_dwordx4 v[200:203], v[120:121], off
	global_load_dwordx4 v[204:207], v[128:129], off
	global_load_dwordx4 v[208:211], v[110:111], off
	global_load_dwordx4 v[212:215], v[110:111], off offset:64
	global_load_dword v224, v[40:41], off offset:-64
	global_load_dwordx4 v[216:219], v[236:237], off
	global_load_dwordx4 v[220:223], v[236:237], off offset:64
	global_load_dword v226, v[40:41], off
	s_add_i32 s47, s47, 1
	s_addk_i32 s64, 0x4000
	s_add_u32 s8, s8, 0x200
	s_addc_u32 s9, s9, 0
	v_lshl_add_u64 v[10:11], v[10:11], 0, s[44:45]
	v_lshl_add_u64 v[12:13], v[12:13], 0, s[44:45]
	v_lshl_add_u64 v[16:17], v[16:17], 0, s[40:41]
	v_lshl_add_u64 v[20:21], v[20:21], 0, s[40:41]
	v_lshl_add_u64 v[24:25], v[24:25], 0, s[40:41]
	v_lshl_add_u64 v[28:29], v[28:29], 0, s[40:41]
	s_cmp_lg_u32 s64, 0x10000
	s_waitcnt vmcnt(21) lgkmcnt(0)
	v_pk_mul_f32 v[6:7], v[160:161], v[60:61] op_sel_hi:[1,0]
	v_pk_mul_f32 v[4:5], v[158:159], v[60:61] op_sel_hi:[1,0]
	v_pk_mul_f32 v[2:3], v[164:165], v[60:61] op_sel_hi:[1,0]
	v_pk_mul_f32 v[0:1], v[162:163], v[60:61] op_sel_hi:[1,0]
	s_waitcnt vmcnt(20)
	v_lshlrev_b32_e32 v76, 16, v30
	v_and_b32_e32 v77, 0xffff0000, v30
	v_lshlrev_b32_e32 v30, 16, v31
	v_and_b32_e32 v31, 0xffff0000, v31
	v_lshlrev_b32_e32 v78, 16, v32
	v_and_b32_e32 v79, 0xffff0000, v32
	v_lshlrev_b32_e32 v32, 16, v33
	v_and_b32_e32 v33, 0xffff0000, v33
	v_pk_mul_f32 v[4:5], v[4:5], v[76:77]
	v_pk_mul_f32 v[6:7], v[6:7], v[30:31]
	v_pk_mul_f32 v[30:31], v[0:1], v[78:79]
	v_pk_mul_f32 v[32:33], v[2:3], v[32:33]
	v_cvt_pk_bf16_f32 v0, v4, v5
	v_cvt_pk_bf16_f32 v1, v6, v7
	v_cvt_pk_bf16_f32 v2, v30, v31
	v_cvt_pk_bf16_f32 v3, v32, v33
	ds_write_b128 v39, v[0:3] offset:8192
	s_waitcnt vmcnt(19)
	v_lshlrev_b32_e32 v80, 16, v62
	v_and_b32_e32 v81, 0xffff0000, v62
	v_lshlrev_b32_e32 v62, 16, v63
	v_and_b32_e32 v63, 0xffff0000, v63
	v_lshlrev_b32_e32 v82, 16, v64
	v_and_b32_e32 v83, 0xffff0000, v64
	v_lshlrev_b32_e32 v64, 16, v65
	v_and_b32_e32 v65, 0xffff0000, v65
	s_waitcnt vmcnt(16)
	v_pk_mul_f32 v[2:3], v[160:161], v[36:37] op_sel_hi:[1,0]
	v_pk_mul_f32 v[0:1], v[158:159], v[36:37] op_sel_hi:[1,0]
	v_pk_mul_f32 v[6:7], v[164:165], v[36:37] op_sel_hi:[1,0]
	v_pk_mul_f32 v[4:5], v[162:163], v[36:37] op_sel_hi:[1,0]
	v_pk_mul_f32 v[0:1], v[0:1], v[80:81]
	v_pk_mul_f32 v[2:3], v[2:3], v[62:63]
	v_pk_mul_f32 v[4:5], v[4:5], v[82:83]
	v_pk_mul_f32 v[6:7], v[6:7], v[64:65]
	v_cvt_pk_bf16_f32 v0, v0, v1
	v_cvt_pk_bf16_f32 v1, v2, v3
	v_cvt_pk_bf16_f32 v2, v4, v5
	v_cvt_pk_bf16_f32 v3, v6, v7
	ds_write_b128 v43, v[0:3] offset:8192
	v_lshlrev_b32_e32 v84, 16, v66
	v_and_b32_e32 v85, 0xffff0000, v66
	v_lshlrev_b32_e32 v66, 16, v67
	v_and_b32_e32 v67, 0xffff0000, v67
	v_lshlrev_b32_e32 v86, 16, v68
	v_and_b32_e32 v87, 0xffff0000, v68
	v_lshlrev_b32_e32 v68, 16, v69
	v_and_b32_e32 v69, 0xffff0000, v69
	s_waitcnt vmcnt(15)
	v_pk_mul_f32 v[2:3], v[160:161], v[38:39] op_sel_hi:[1,0]
	v_pk_mul_f32 v[0:1], v[158:159], v[38:39] op_sel_hi:[1,0]
	v_pk_mul_f32 v[6:7], v[164:165], v[38:39] op_sel_hi:[1,0]
	v_pk_mul_f32 v[4:5], v[162:163], v[38:39] op_sel_hi:[1,0]
	v_pk_mul_f32 v[0:1], v[0:1], v[84:85]
	v_pk_mul_f32 v[2:3], v[2:3], v[66:67]
	v_pk_mul_f32 v[4:5], v[4:5], v[86:87]
	v_pk_mul_f32 v[6:7], v[6:7], v[68:69]
	v_cvt_pk_bf16_f32 v0, v0, v1
	v_cvt_pk_bf16_f32 v1, v2, v3
	v_cvt_pk_bf16_f32 v2, v4, v5
	v_cvt_pk_bf16_f32 v3, v6, v7
	ds_write_b128 v45, v[0:3] offset:8192
	v_lshlrev_b32_e32 v88, 16, v70
	v_and_b32_e32 v89, 0xffff0000, v70
	v_lshlrev_b32_e32 v70, 16, v71
	v_and_b32_e32 v71, 0xffff0000, v71
	v_lshlrev_b32_e32 v90, 16, v72
	v_and_b32_e32 v91, 0xffff0000, v72
	v_lshlrev_b32_e32 v72, 16, v73
	v_and_b32_e32 v73, 0xffff0000, v73
	s_waitcnt vmcnt(14)
	v_pk_mul_f32 v[2:3], v[160:161], v[44:45] op_sel_hi:[1,0]
	v_pk_mul_f32 v[0:1], v[158:159], v[44:45] op_sel_hi:[1,0]
	v_pk_mul_f32 v[6:7], v[164:165], v[44:45] op_sel_hi:[1,0]
	v_pk_mul_f32 v[4:5], v[162:163], v[44:45] op_sel_hi:[1,0]
	v_pk_mul_f32 v[0:1], v[0:1], v[88:89]
	v_pk_mul_f32 v[2:3], v[2:3], v[70:71]
	v_pk_mul_f32 v[4:5], v[4:5], v[90:91]
	v_pk_mul_f32 v[6:7], v[6:7], v[72:73]
	v_cvt_pk_bf16_f32 v0, v0, v1
	v_cvt_pk_bf16_f32 v1, v2, v3
	v_cvt_pk_bf16_f32 v2, v4, v5
	v_cvt_pk_bf16_f32 v3, v6, v7
	ds_write_b128 v37, v[0:3] offset:8192
	s_waitcnt lgkmcnt(0)
	s_barrier
	ds_read_b128 v[30:33], v57 offset:8192
	ds_read_b128 v[36:39], v57 offset:8256
	ds_read_b128 v[62:65], v57 offset:12544
	ds_read_b128 v[66:69], v57 offset:12608
	ds_read_b128 v[74:77], v57 offset:16896
	ds_read_b128 v[78:81], v57 offset:16960
	ds_read_b128 v[86:89], v57 offset:21248
	ds_read_b128 v[90:93], v57 offset:21312
	v_lshl_add_u64 v[42:43], v[58:59], 1, s[38:39]
	v_lshl_add_u64 v[58:59], v[94:95], 1, s[38:39]
	s_waitcnt vmcnt(13) lgkmcnt(7)
	v_mfma_f32_16x16x32_bf16 v[44:47], v[30:33], v[176:179], 0
	s_waitcnt lgkmcnt(5)
	v_mfma_f32_16x16x32_bf16 v[70:73], v[62:65], v[176:179], 0
	s_waitcnt lgkmcnt(3)
	v_mfma_f32_16x16x32_bf16 v[82:85], v[74:77], v[176:179], 0
	s_waitcnt lgkmcnt(1)
	v_mfma_f32_16x16x32_bf16 v[0:3], v[86:89], v[176:179], 0
	s_waitcnt vmcnt(12)
	v_mfma_f32_16x16x32_bf16 v[30:33], v[30:33], v[180:183], 0
	v_mfma_f32_16x16x32_bf16 v[62:65], v[62:65], v[180:183], 0
	v_mfma_f32_16x16x32_bf16 v[74:77], v[74:77], v[180:183], 0
	v_mfma_f32_16x16x32_bf16 v[4:7], v[86:89], v[180:183], 0
	s_waitcnt vmcnt(11)
	v_mfma_f32_16x16x32_bf16 v[42:45], v[36:39], v[184:187], v[44:47]
	v_mfma_f32_16x16x32_bf16 v[70:73], v[66:69], v[184:187], v[70:73]
	s_nop 1
	v_add_co_u32_e32 v46, vcc, s62, v98
	v_mfma_f32_16x16x32_bf16 v[82:85], v[78:81], v[184:187], v[82:85]
	s_nop 0
	v_addc_co_u32_e32 v47, vcc, 0, v99, vcc
	v_add_co_u32_e32 v58, vcc, s61, v34
	s_waitcnt lgkmcnt(0)
	v_mfma_f32_16x16x32_bf16 v[0:3], v[90:93], v[184:187], v[0:3]
	v_lshl_add_u64 v[94:95], v[100:101], 1, s[38:39]
	v_lshl_add_u64 v[96:97], v[102:103], 1, s[38:39]
	v_addc_co_u32_e32 v59, vcc, 0, v35, vcc
	s_waitcnt vmcnt(10)
	v_mfma_f32_16x16x32_bf16 v[30:33], v[36:39], v[188:191], v[30:33]
	v_add_co_u32_e32 v34, vcc, s62, v34
	v_mfma_f32_16x16x32_bf16 v[36:39], v[66:69], v[188:191], v[62:65]
	s_nop 0
	v_addc_co_u32_e32 v35, vcc, 0, v35, vcc
	s_nop 0
	v_mfma_f32_16x16x32_bf16 v[66:69], v[78:81], v[188:191], v[74:77]
	s_nop 2
	v_mfma_f32_16x16x32_bf16 v[4:7], v[90:93], v[188:191], v[4:7]
	ds_read_b128 v[78:81], v57 offset:8320
	ds_read_b128 v[86:89], v57 offset:8384
	ds_read_b128 v[90:93], v57 offset:12672
	ds_read_b128 v[94:97], v57 offset:12736
	ds_read_b128 v[98:101], v57 offset:17024
	ds_read_b128 v[102:105], v57 offset:17088
	ds_read_b128 v[116:119], v57 offset:21376
	ds_read_b128 v[124:127], v57 offset:21440
	s_waitcnt vmcnt(9) lgkmcnt(7)
	v_mfma_f32_16x16x32_bf16 v[42:45], v[78:81], v[192:195], v[42:45]
	s_waitcnt lgkmcnt(5)
	v_mfma_f32_16x16x32_bf16 v[70:73], v[90:93], v[192:195], v[70:73]
	s_waitcnt lgkmcnt(3)
	v_mfma_f32_16x16x32_bf16 v[82:85], v[98:101], v[192:195], v[82:85]
	s_waitcnt lgkmcnt(1)
	v_mfma_f32_16x16x32_bf16 v[0:3], v[116:119], v[192:195], v[0:3]
	s_waitcnt vmcnt(5)
	v_lshlrev_b32_e32 v110, 16, v208
	v_mfma_f32_16x16x32_bf16 v[30:33], v[78:81], v[196:199], v[30:33]
	v_and_b32_e32 v111, 0xffff0000, v208
	s_waitcnt vmcnt(4)
	v_lshlrev_b32_e32 v106, 16, v214
	v_mfma_f32_16x16x32_bf16 v[42:45], v[86:89], v[200:203], v[42:45]
	v_mfma_f32_16x16x32_bf16 v[70:73], v[94:97], v[200:203], v[70:73]
	v_mfma_f32_16x16x32_bf16 v[82:85], v[102:105], v[200:203], v[82:85]
	s_waitcnt vmcnt(3)
	s_nop 4
	v_pk_add_f32 v[44:45], v[44:45], v[224:225] op_sel_hi:[1,0]
	s_waitcnt lgkmcnt(0)
	v_mfma_f32_16x16x32_bf16 v[0:3], v[124:127], v[200:203], v[0:3]
	v_add_f32_e64 v42, v42, v224
	v_add_f32_e64 v43, v43, v224
	v_pk_add_f32 v[72:73], v[72:73], v[224:225] op_sel_hi:[1,0]
	v_pk_add_f32 v[70:71], v[70:71], v[224:225] op_sel_hi:[1,0]
	v_mfma_f32_16x16x32_bf16 v[36:39], v[90:93], v[196:199], v[36:39]
	v_lshlrev_b32_e32 v90, 16, v209
	v_and_b32_e32 v91, 0xffff0000, v209
	v_lshlrev_b32_e32 v92, 16, v210
	v_mfma_f32_16x16x32_bf16 v[66:69], v[98:101], v[196:199], v[66:69]
	v_and_b32_e32 v93, 0xffff0000, v210
	v_lshlrev_b32_e32 v98, 16, v211
	v_and_b32_e32 v99, 0xffff0000, v211
	v_lshlrev_b32_e32 v100, 16, v212
	v_and_b32_e32 v101, 0xffff0000, v212
	v_lshlrev_b32_e32 v62, 16, v213
	v_and_b32_e32 v63, 0xffff0000, v213
	v_and_b32_e32 v107, 0xffff0000, v214
	v_lshlrev_b32_e32 v64, 16, v215
	v_and_b32_e32 v65, 0xffff0000, v215
	v_pk_add_f32 v[84:85], v[84:85], v[224:225] op_sel_hi:[1,0]
	v_pk_add_f32 v[82:83], v[82:83], v[224:225] op_sel_hi:[1,0]
	v_pk_add_f32 v[2:3], v[2:3], v[224:225] op_sel_hi:[1,0]
	v_pk_add_f32 v[0:1], v[0:1], v[224:225] op_sel_hi:[1,0]
	v_pk_mul_f32 v[42:43], v[42:43], v[110:111]
	v_pk_mul_f32 v[44:45], v[44:45], v[90:91]
	v_pk_mul_f32 v[70:71], v[70:71], v[92:93]
	v_pk_mul_f32 v[72:73], v[72:73], v[98:99]
	v_pk_mul_f32 v[82:83], v[82:83], v[100:101]
	v_pk_mul_f32 v[62:63], v[84:85], v[62:63]
	v_pk_mul_f32 v[84:85], v[0:1], v[106:107]
	v_pk_mul_f32 v[64:65], v[2:3], v[64:65]
	v_cvt_pk_bf16_f32 v0, v42, v43
	v_cvt_pk_bf16_f32 v1, v44, v45
	v_cvt_pk_bf16_f32 v2, v70, v71
	v_cvt_pk_bf16_f32 v3, v72, v73
	v_cvt_pk_bf16_f32 v42, v82, v83
	v_cvt_pk_bf16_f32 v43, v62, v63
	v_cvt_pk_bf16_f32 v44, v84, v85
	v_cvt_pk_bf16_f32 v45, v64, v65
	global_store_dwordx4 v[46:47], v[0:3], off
	global_store_dwordx4 v[46:47], v[42:45], off offset:64
	s_nop 0
	v_mfma_f32_16x16x32_bf16 v[4:7], v[116:119], v[196:199], v[4:7]
	s_waitcnt vmcnt(2)
	v_lshlrev_b32_e32 v58, 16, v216
	v_mfma_f32_16x16x32_bf16 v[30:33], v[86:89], v[204:207], v[30:33]
	v_and_b32_e32 v59, 0xffff0000, v216
	v_lshlrev_b32_e32 v0, 16, v217
	v_and_b32_e32 v1, 0xffff0000, v217
	v_mfma_f32_16x16x32_bf16 v[36:39], v[94:97], v[204:207], v[36:39]
	v_lshlrev_b32_e32 v62, 16, v218
	s_nop 2
	v_pk_add_f32 v[32:33], v[32:33], v[226:227] op_sel_hi:[1,0]
	v_pk_add_f32 v[30:31], v[30:31], v[226:227] op_sel_hi:[1,0]
	v_mfma_f32_16x16x32_bf16 v[44:47], v[102:105], v[204:207], v[66:69]
	v_and_b32_e32 v63, 0xffff0000, v218
	v_pk_add_f32 v[38:39], v[38:39], v[226:227] op_sel_hi:[1,0]
	v_pk_add_f32 v[36:37], v[36:37], v[226:227] op_sel_hi:[1,0]
	v_mfma_f32_16x16x32_bf16 v[4:7], v[124:127], v[204:207], v[4:7]
	v_lshlrev_b32_e32 v2, 16, v219
	v_and_b32_e32 v3, 0xffff0000, v219
	s_nop 1
	v_pk_add_f32 v[46:47], v[46:47], v[226:227] op_sel_hi:[1,0]
	v_pk_add_f32 v[44:45], v[44:45], v[226:227] op_sel_hi:[1,0]
	s_waitcnt vmcnt(2)
	v_lshlrev_b32_e32 v64, 16, v220
	v_pk_add_f32 v[6:7], v[6:7], v[226:227] op_sel_hi:[1,0]
	v_pk_add_f32 v[4:5], v[4:5], v[226:227] op_sel_hi:[1,0]
	v_and_b32_e32 v65, 0xffff0000, v220
	v_lshlrev_b32_e32 v40, 16, v221
	v_and_b32_e32 v41, 0xffff0000, v221
	v_lshlrev_b32_e32 v66, 16, v222
	v_and_b32_e32 v67, 0xffff0000, v222
	v_lshlrev_b32_e32 v42, 16, v223
	v_and_b32_e32 v43, 0xffff0000, v223
	v_pk_mul_f32 v[30:31], v[30:31], v[58:59]
	v_pk_mul_f32 v[32:33], v[32:33], v[0:1]
	v_pk_mul_f32 v[36:37], v[36:37], v[62:63]
	v_pk_mul_f32 v[38:39], v[38:39], v[2:3]
	v_pk_mul_f32 v[44:45], v[44:45], v[64:65]
	v_pk_mul_f32 v[40:41], v[46:47], v[40:41]
	v_pk_mul_f32 v[46:47], v[4:5], v[66:67]
	v_pk_mul_f32 v[42:43], v[6:7], v[42:43]
	v_cvt_pk_bf16_f32 v0, v30, v31
	v_cvt_pk_bf16_f32 v1, v32, v33
	v_cvt_pk_bf16_f32 v2, v36, v37
	v_cvt_pk_bf16_f32 v3, v38, v39
	v_cvt_pk_bf16_f32 v4, v44, v45
	v_cvt_pk_bf16_f32 v5, v40, v41
	v_cvt_pk_bf16_f32 v6, v46, v47
	v_cvt_pk_bf16_f32 v7, v42, v43
	global_store_dwordx4 v[34:35], v[0:3], off
	global_store_dwordx4 v[34:35], v[4:7], off offset:64
	s_cbranch_scc1 .LBB0_396
	v_mov_b32_e32 v0, v174
	s_barrier
	s_and_b32 s10, s10, 0xf80
	s_lshl_b32 s46, s46, 19
	v_ashrrev_i32_e32 v1, 2, v0
	s_add_u32 s8, s12, s46
	v_lshlrev_b32_e32 v0, 4, v0
	s_addc_u32 s9, s13, 0
	v_and_b32_e32 v60, 0x1f0, v0
	v_and_b32_e32 v66, -8, v1
	v_lshl_add_u64 v[64:65], s[8:9], 0, v[60:61]
	s_add_u32 s8, s66, s46
	s_addc_u32 s9, s67, 0
	v_or_b32_e32 v80, 1, v66
	v_or_b32_e32 v78, 2, v66
	v_or_b32_e32 v76, 3, v66
	v_or_b32_e32 v74, 4, v66
	v_or_b32_e32 v72, 5, v66
	v_or_b32_e32 v70, 6, v66
	v_or_b32_e32 v68, 7, v1
	v_lshl_add_u64 v[62:63], s[8:9], 0, v[60:61]
	s_mov_b64 s[8:9], -1
	s_cmp_lg_u32 s33, 0
	v_add_u32_e32 v124, -3, v66
	v_add_u32_e32 v123, -2, v66
	v_add_u32_e32 v125, -1, v66
	v_add_u32_e32 v122, s10, v66
	v_ashrrev_i32_e32 v67, 31, v66
	v_add_u32_e32 v121, s10, v80
	v_ashrrev_i32_e32 v81, 31, v80
	v_add_u32_e32 v120, s10, v78
	v_ashrrev_i32_e32 v79, 31, v78
	v_add_u32_e32 v119, s10, v76
	v_ashrrev_i32_e32 v77, 31, v76
	v_add_u32_e32 v118, s10, v74
	v_ashrrev_i32_e32 v75, 31, v74
	v_add_u32_e32 v117, s10, v72
	v_ashrrev_i32_e32 v73, 31, v72
	v_add_u32_e32 v116, s10, v70
	v_ashrrev_i32_e32 v71, 31, v70
	v_add_u32_e32 v60, s10, v68
	s_cbranch_scc0 .LBB0_399
	s_sub_i32 s8, 0, s10
	v_max_i32_e32 v0, s8, v124
	v_ashrrev_i32_e32 v1, 31, v0
	v_lshlrev_b64 v[0:1], 12, v[0:1]
	v_lshl_add_u64 v[22:23], v[64:65], 0, v[0:1]
	v_max_i32_e32 v0, s8, v123
	v_ashrrev_i32_e32 v1, 31, v0
	v_lshlrev_b64 v[0:1], 12, v[0:1]
	v_lshl_add_u64 v[28:29], v[64:65], 0, v[0:1]
	v_max_i32_e32 v0, s8, v125
	v_ashrrev_i32_e32 v1, 31, v0
	global_load_dwordx4 v[4:7], v[22:23], off offset:512
	v_lshlrev_b64 v[0:1], 12, v[0:1]
	global_load_dwordx4 v[8:11], v[28:29], off offset:512
	v_lshl_add_u64 v[30:31], v[64:65], 0, v[0:1]
	v_max_i32_e32 v0, s8, v66
	global_load_dwordx4 v[12:15], v[30:31], off offset:512
	v_ashrrev_i32_e32 v1, 31, v0
	v_lshlrev_b64 v[0:1], 12, v[0:1]
	v_lshl_add_u64 v[20:21], v[64:65], 0, v[0:1]
	global_load_dwordx4 v[0:3], v[20:21], off offset:512
	v_min_i32_e32 v17, 3, v122
	v_max_i32_e32 v16, s8, v80
	v_max_i32_e32 v18, s8, v78
	v_max_i32_e32 v24, s8, v76
	v_max_i32_e32 v26, s8, v74
	v_max_i32_e32 v32, s8, v72
	v_add_u32_e32 v35, 1, v17
	v_ashrrev_i32_e32 v17, 31, v16
	v_ashrrev_i32_e32 v19, 31, v18
	v_ashrrev_i32_e32 v25, 31, v24
	v_ashrrev_i32_e32 v27, 31, v26
	v_ashrrev_i32_e32 v33, 31, v32
	v_lshlrev_b64 v[16:17], 12, v[16:17]
	v_lshlrev_b64 v[18:19], 12, v[18:19]
	v_lshlrev_b64 v[24:25], 12, v[24:25]
	v_lshlrev_b64 v[26:27], 12, v[26:27]
	v_lshlrev_b64 v[40:41], 12, v[32:33]
	v_lshl_add_u64 v[32:33], v[64:65], 0, v[16:17]
	v_lshl_add_u64 v[84:85], v[64:65], 0, v[18:19]
	v_lshl_add_u64 v[58:59], v[64:65], 0, v[24:25]
	v_lshl_add_u64 v[56:57], v[64:65], 0, v[26:27]
	global_load_dwordx4 v[24:27], v[32:33], off offset:512
	global_load_dwordx4 v[16:19], v[84:85], off offset:512
	global_load_dwordx4 v[48:51], v[22:23], off offset:1024
	global_load_dwordx4 v[44:47], v[28:29], off offset:1024
	v_cvt_f32_i32_e32 v35, v35
	v_max_i32_e32 v36, s8, v70
	v_max_i32_e32 v38, s8, v68
	v_ashrrev_i32_e32 v37, 31, v36
	v_div_scale_f32 v22, s[46:47], v35, v35, 1.0
	v_rcp_f32_e32 v23, v22
	v_ashrrev_i32_e32 v39, 31, v38
	v_div_scale_f32 v28, vcc, 1.0, v35, 1.0
	v_fma_f32 v29, -v22, v23, 1.0
	v_fmac_f32_e32 v23, v29, v23
	v_lshlrev_b64 v[36:37], 12, v[36:37]
	v_lshlrev_b64 v[38:39], 12, v[38:39]
	v_mul_f32_e32 v29, v28, v23
	v_lshl_add_u64 v[54:55], v[64:65], 0, v[40:41]
	v_lshl_add_u64 v[52:53], v[64:65], 0, v[36:37]
	v_lshl_add_u64 v[82:83], v[64:65], 0, v[38:39]
	global_load_dwordx4 v[40:43], v[30:31], off offset:1024
	global_load_dwordx4 v[36:39], v[20:21], off offset:1024
	v_fma_f32 v30, -v22, v29, v28
	v_fmac_f32_e32 v29, v30, v23
	v_add_u32_e32 v34, s10, v124
	v_fma_f32 v22, -v22, v29, v28
	v_div_fmas_f32 v22, v22, v23, v29
	v_cmp_lt_i32_e32 vcc, -1, v34
	s_waitcnt vmcnt(6)
	v_lshlrev_b32_e32 v134, 16, v1
	v_cndmask_b32_e32 v23, 0, v7, vcc
	v_cndmask_b32_e32 v28, 0, v6, vcc
	v_cndmask_b32_e32 v5, 0, v5, vcc
	v_cndmask_b32_e32 v6, 0, v4, vcc
	v_cmp_lt_i32_e32 vcc, -2, v34
	v_lshlrev_b32_e32 v128, 16, v5
	v_and_b32_e32 v129, 0xffff0000, v5
	v_cndmask_b32_e32 v29, 0, v11, vcc
	v_cndmask_b32_e32 v10, 0, v10, vcc
	v_cndmask_b32_e32 v11, 0, v9, vcc
	v_cndmask_b32_e32 v8, 0, v8, vcc
	v_cmp_lt_i32_e32 vcc, -3, v34
	v_lshlrev_b32_e32 v106, 16, v8
	v_and_b32_e32 v107, 0xffff0000, v8
	v_cndmask_b32_e32 v9, 0, v12, vcc
	v_cndmask_b32_e32 v13, 0, v13, vcc
	v_lshlrev_b32_e32 v108, 16, v9
	v_and_b32_e32 v109, 0xffff0000, v9
	v_pk_add_f32 v[8:9], v[128:129], 0 op_sel_hi:[1,0]
	v_lshlrev_b32_e32 v130, 16, v11
	v_and_b32_e32 v131, 0xffff0000, v11
	v_pk_add_f32 v[8:9], v[8:9], v[130:131]
	v_lshlrev_b32_e32 v132, 16, v13
	v_and_b32_e32 v133, 0xffff0000, v13
	v_lshlrev_b32_e32 v86, 16, v6
	v_and_b32_e32 v87, 0xffff0000, v6
	v_pk_add_f32 v[8:9], v[8:9], v[132:133]
	v_and_b32_e32 v135, 0xffff0000, v1
	v_lshlrev_b32_e32 v138, 16, v28
	v_and_b32_e32 v139, 0xffff0000, v28
	v_lshlrev_b32_e32 v148, 16, v23
	v_and_b32_e32 v149, 0xffff0000, v23
	v_cndmask_b32_e32 v15, 0, v15, vcc
	v_cndmask_b32_e32 v14, 0, v14, vcc
	v_div_fixup_f32 v4, v22, v35, 1.0
	v_pk_add_f32 v[6:7], v[86:87], 0 op_sel_hi:[1,0]
	v_pk_add_f32 v[136:137], v[8:9], v[134:135]
	v_pk_add_f32 v[8:9], v[138:139], 0 op_sel_hi:[1,0]
	v_lshlrev_b32_e32 v140, 16, v10
	v_and_b32_e32 v141, 0xffff0000, v10
	v_pk_add_f32 v[10:11], v[148:149], 0 op_sel_hi:[1,0]
	v_lshlrev_b32_e32 v150, 16, v29
	v_and_b32_e32 v151, 0xffff0000, v29
	v_pk_add_f32 v[6:7], v[6:7], v[106:107]
	v_lshlrev_b32_e32 v110, 16, v0
	v_and_b32_e32 v111, 0xffff0000, v0
	v_pk_fma_f32 v[0:1], v[4:5], v[136:137], v[134:135] op_sel_hi:[0,1,1] neg_lo:[0,0,1] neg_hi:[0,0,1]
	v_pk_add_f32 v[8:9], v[8:9], v[140:141]
	v_lshlrev_b32_e32 v142, 16, v14
	v_and_b32_e32 v143, 0xffff0000, v14
	v_pk_add_f32 v[10:11], v[10:11], v[150:151]
	v_lshlrev_b32_e32 v152, 16, v15
	v_and_b32_e32 v153, 0xffff0000, v15
	v_pk_add_f32 v[6:7], v[6:7], v[108:109]
	v_pk_add_f32 v[8:9], v[8:9], v[142:143]
	v_lshlrev_b32_e32 v144, 16, v2
	v_and_b32_e32 v145, 0xffff0000, v2
	v_pk_add_f32 v[10:11], v[10:11], v[152:153]
	v_lshlrev_b32_e32 v154, 16, v3
	v_and_b32_e32 v155, 0xffff0000, v3
	v_cvt_pk_bf16_f32 v91, v0, v1
	v_min_i32_e32 v0, 3, v121
	v_pk_add_f32 v[126:127], v[6:7], v[110:111]
	v_pk_add_f32 v[146:147], v[8:9], v[144:145]
	v_pk_add_f32 v[156:157], v[10:11], v[154:155]
	v_add_u32_e32 v0, 1, v0
	v_pk_fma_f32 v[6:7], v[4:5], v[126:127], v[110:111] op_sel_hi:[0,1,1] neg_lo:[0,0,1] neg_hi:[0,0,1]
	v_pk_fma_f32 v[8:9], v[4:5], v[146:147], v[144:145] op_sel_hi:[0,1,1] neg_lo:[0,0,1] neg_hi:[0,0,1]
	v_pk_fma_f32 v[2:3], v[4:5], v[156:157], v[154:155] op_sel_hi:[0,1,1] neg_lo:[0,0,1] neg_hi:[0,0,1]
	v_cvt_f32_i32_e32 v69, v0
	v_lshlrev_b64 v[0:1], 12, v[66:67]
	v_cvt_pk_bf16_f32 v90, v6, v7
	v_cvt_pk_bf16_f32 v92, v8, v9
	v_cvt_pk_bf16_f32 v93, v2, v3
	v_lshl_add_u64 v[88:89], v[62:63], 0, v[0:1]
	global_load_dwordx4 v[32:35], v[32:33], off offset:1024
	s_nop 0
	global_load_dwordx4 v[28:31], v[84:85], off offset:1024
	global_load_dwordx4 v[94:97], v[58:59], off offset:512
	global_load_dwordx4 v[20:23], v[58:59], off offset:1024
	global_load_dwordx4 v[98:101], v[56:57], off offset:512
	global_load_dwordx4 v[12:15], v[56:57], off offset:1024
	global_load_dwordx4 v[102:105], v[54:55], off offset:512
	global_load_dwordx4 v[8:11], v[54:55], off offset:1024
	s_nop 0
	global_load_dwordx4 v[56:59], v[52:53], off offset:512
	global_load_dwordx4 v[4:7], v[52:53], off offset:1024
	s_nop 0
	global_load_dwordx4 v[52:55], v[82:83], off offset:512
	global_load_dwordx4 v[0:3], v[82:83], off offset:1024
	v_div_scale_f32 v158, s[46:47], v69, v69, 1.0
	v_rcp_f32_e32 v159, v158
	global_store_dwordx4 v[88:89], v[90:93], off offset:512
	v_fma_f32 v82, -v158, v159, 1.0
	v_fmac_f32_e32 v159, v82, v159
	v_div_scale_f32 v82, vcc, 1.0, v69, 1.0
	v_mul_f32_e32 v83, v82, v159
	v_fma_f32 v84, -v158, v83, v82
	v_fmac_f32_e32 v83, v84, v159
	v_fma_f32 v82, -v158, v83, v82
	v_pk_add_f32 v[92:93], v[136:137], v[128:129] neg_lo:[0,1] neg_hi:[0,1]
	s_waitcnt vmcnt(18)
	v_lshlrev_b32_e32 v136, 16, v26
	v_and_b32_e32 v137, 0xffff0000, v26
	v_min_i32_e32 v26, 3, v120
	v_div_fmas_f32 v82, v82, v159, v83
	v_add_u32_e32 v26, 1, v26
	v_div_fixup_f32 v82, v82, v69, 1.0
	v_cvt_f32_i32_e32 v69, v26
	v_pk_add_f32 v[84:85], v[126:127], v[86:87] neg_lo:[0,1] neg_hi:[0,1]
	v_lshlrev_b32_e32 v126, 16, v25
	v_and_b32_e32 v127, 0xffff0000, v25
	v_lshlrev_b32_e32 v90, 16, v24
	v_and_b32_e32 v91, 0xffff0000, v24
	v_pk_add_f32 v[92:93], v[92:93], v[126:127]
	v_pk_add_f32 v[24:25], v[146:147], v[138:139] neg_lo:[0,1] neg_hi:[0,1]
	v_pk_fma_f32 v[128:129], v[82:83], v[92:93], v[126:127] op_sel_hi:[0,1,1] neg_lo:[0,0,1] neg_hi:[0,0,1]
	v_pk_add_f32 v[138:139], v[24:25], v[136:137]
	v_pk_add_f32 v[24:25], v[156:157], v[148:149] neg_lo:[0,1] neg_hi:[0,1]
	v_lshlrev_b32_e32 v148, 16, v27
	v_and_b32_e32 v149, 0xffff0000, v27
	v_pk_add_f32 v[156:157], v[24:25], v[148:149]
	v_cvt_pk_bf16_f32 v25, v128, v129
	v_div_scale_f32 v128, s[46:47], v69, v69, 1.0
	v_pk_add_f32 v[84:85], v[84:85], v[90:91]
	v_rcp_f32_e32 v129, v128
	v_pk_fma_f32 v[86:87], v[82:83], v[84:85], v[90:91] op_sel_hi:[0,1,1] neg_lo:[0,0,1] neg_hi:[0,0,1]
	v_pk_fma_f32 v[146:147], v[82:83], v[138:139], v[136:137] op_sel_hi:[0,1,1] neg_lo:[0,0,1] neg_hi:[0,0,1]
	v_pk_fma_f32 v[82:83], v[82:83], v[156:157], v[148:149] op_sel_hi:[0,1,1] neg_lo:[0,0,1] neg_hi:[0,0,1]
	v_cvt_pk_bf16_f32 v27, v82, v83
	v_lshlrev_b64 v[82:83], 12, v[80:81]
	v_cvt_pk_bf16_f32 v24, v86, v87
	v_cvt_pk_bf16_f32 v26, v146, v147
	v_lshl_add_u64 v[86:87], v[62:63], 0, v[82:83]
	global_store_dwordx4 v[86:87], v[24:27], off offset:512
	s_waitcnt vmcnt(18)
	v_lshlrev_b32_e32 v146, 16, v19
	v_and_b32_e32 v147, 0xffff0000, v19
	v_fma_f32 v24, -v128, v129, 1.0
	v_fmac_f32_e32 v129, v24, v129
	v_div_scale_f32 v24, vcc, 1.0, v69, 1.0
	v_mul_f32_e32 v25, v24, v129
	v_fma_f32 v26, -v128, v25, v24
	v_fmac_f32_e32 v25, v26, v129
	v_fma_f32 v24, -v128, v25, v24
	v_pk_add_f32 v[26:27], v[84:85], v[106:107] neg_lo:[0,1] neg_hi:[0,1]
	v_pk_add_f32 v[84:85], v[92:93], v[130:131] neg_lo:[0,1] neg_hi:[0,1]
	v_lshlrev_b32_e32 v130, 16, v18
	v_and_b32_e32 v131, 0xffff0000, v18
	v_min_i32_e32 v18, 3, v119
	v_div_fmas_f32 v24, v24, v129, v25
	v_add_u32_e32 v18, 1, v18
	v_div_fixup_f32 v24, v24, v69, 1.0
	v_cvt_f32_i32_e32 v69, v18
	v_lshlrev_b32_e32 v106, 16, v16
	v_and_b32_e32 v107, 0xffff0000, v16
	v_pk_add_f32 v[26:27], v[26:27], v[106:107]
	v_lshlrev_b32_e32 v128, 16, v17
	v_and_b32_e32 v129, 0xffff0000, v17
	v_pk_add_f32 v[16:17], v[138:139], v[140:141] neg_lo:[0,1] neg_hi:[0,1]
	v_pk_fma_f32 v[82:83], v[24:25], v[26:27], v[106:107] op_sel_hi:[0,1,1] neg_lo:[0,0,1] neg_hi:[0,0,1]
	v_pk_add_f32 v[138:139], v[16:17], v[130:131]
	v_pk_add_f32 v[16:17], v[156:157], v[150:151] neg_lo:[0,1] neg_hi:[0,1]
	v_pk_add_f32 v[92:93], v[84:85], v[128:129]
	v_pk_add_f32 v[150:151], v[16:17], v[146:147]
	v_cvt_pk_bf16_f32 v16, v82, v83
	v_div_scale_f32 v82, s[46:47], v69, v69, 1.0
	v_rcp_f32_e32 v83, v82
	v_pk_fma_f32 v[84:85], v[24:25], v[92:93], v[128:129] op_sel_hi:[0,1,1] neg_lo:[0,0,1] neg_hi:[0,0,1]
	v_pk_fma_f32 v[140:141], v[24:25], v[138:139], v[130:131] op_sel_hi:[0,1,1] neg_lo:[0,0,1] neg_hi:[0,0,1]
	v_pk_fma_f32 v[24:25], v[24:25], v[150:151], v[146:147] op_sel_hi:[0,1,1] neg_lo:[0,0,1] neg_hi:[0,0,1]
	v_cvt_pk_bf16_f32 v19, v24, v25
	v_lshlrev_b64 v[24:25], 12, v[78:79]
	v_cvt_pk_bf16_f32 v17, v84, v85
	v_cvt_pk_bf16_f32 v18, v140, v141
	v_lshl_add_u64 v[84:85], v[62:63], 0, v[24:25]
	global_store_dwordx4 v[84:85], v[16:19], off offset:512
	v_pk_add_f32 v[140:141], v[150:151], v[152:153] neg_lo:[0,1] neg_hi:[0,1]
	s_nop 0
	v_fma_f32 v16, -v82, v83, 1.0
	v_fmac_f32_e32 v83, v16, v83
	v_div_scale_f32 v16, vcc, 1.0, v69, 1.0
	v_mul_f32_e32 v17, v16, v83
	v_fma_f32 v18, -v82, v17, v16
	v_fmac_f32_e32 v17, v18, v83
	v_fma_f32 v16, -v82, v17, v16
	v_div_fmas_f32 v16, v16, v83, v17
	v_pk_add_f32 v[18:19], v[26:27], v[108:109] neg_lo:[0,1] neg_hi:[0,1]
	s_waitcnt vmcnt(12)
	v_lshlrev_b32_e32 v108, 16, v94
	v_and_b32_e32 v109, 0xffff0000, v94
	v_div_fixup_f32 v16, v16, v69, 1.0
	v_pk_add_f32 v[24:25], v[18:19], v[108:109]
	v_pk_add_f32 v[26:27], v[92:93], v[132:133] neg_lo:[0,1] neg_hi:[0,1]
	v_lshlrev_b32_e32 v132, 16, v95
	v_and_b32_e32 v133, 0xffff0000, v95
	v_pk_add_f32 v[92:93], v[138:139], v[142:143] neg_lo:[0,1] neg_hi:[0,1]
	v_lshlrev_b32_e32 v138, 16, v96
	v_and_b32_e32 v139, 0xffff0000, v96
	v_lshlrev_b32_e32 v142, 16, v97
	v_and_b32_e32 v143, 0xffff0000, v97
	v_pk_fma_f32 v[18:19], v[16:17], v[24:25], v[108:109] op_sel_hi:[0,1,1] neg_lo:[0,0,1] neg_hi:[0,0,1]
	v_pk_add_f32 v[26:27], v[26:27], v[132:133]
	v_pk_add_f32 v[92:93], v[92:93], v[138:139]
	v_pk_add_f32 v[96:97], v[140:141], v[142:143]
	v_pk_fma_f32 v[82:83], v[16:17], v[26:27], v[132:133] op_sel_hi:[0,1,1] neg_lo:[0,0,1] neg_hi:[0,0,1]
	v_pk_fma_f32 v[94:95], v[16:17], v[92:93], v[138:139] op_sel_hi:[0,1,1] neg_lo:[0,0,1] neg_hi:[0,0,1]
	v_pk_fma_f32 v[140:141], v[16:17], v[96:97], v[142:143] op_sel_hi:[0,1,1] neg_lo:[0,0,1] neg_hi:[0,0,1]
	v_cvt_pk_bf16_f32 v16, v18, v19
	v_min_i32_e32 v18, 3, v118
	v_add_u32_e32 v18, 1, v18
	v_cvt_f32_i32_e32 v69, v18
	v_cvt_pk_bf16_f32 v18, v94, v95
	v_cvt_pk_bf16_f32 v17, v82, v83
	v_lshlrev_b64 v[82:83], 12, v[76:77]
	v_div_scale_f32 v94, s[46:47], v69, v69, 1.0
	v_rcp_f32_e32 v95, v94
	v_cvt_pk_bf16_f32 v19, v140, v141
	v_lshl_add_u64 v[82:83], v[62:63], 0, v[82:83]
	global_store_dwordx4 v[82:83], v[16:19], off offset:512
	v_pk_add_f32 v[92:93], v[92:93], v[144:145] neg_lo:[0,1] neg_hi:[0,1]
	v_pk_add_f32 v[96:97], v[96:97], v[154:155] neg_lo:[0,1] neg_hi:[0,1]
	v_fma_f32 v16, -v94, v95, 1.0
	v_fmac_f32_e32 v95, v16, v95
	v_div_scale_f32 v16, vcc, 1.0, v69, 1.0
	v_mul_f32_e32 v17, v16, v95
	v_fma_f32 v18, -v94, v17, v16
	v_fmac_f32_e32 v17, v18, v95
	v_fma_f32 v16, -v94, v17, v16
	v_div_fmas_f32 v16, v16, v95, v17
	v_pk_add_f32 v[18:19], v[24:25], v[110:111] neg_lo:[0,1] neg_hi:[0,1]
	s_waitcnt vmcnt(11)
	v_lshlrev_b32_e32 v24, 16, v98
	v_and_b32_e32 v25, 0xffff0000, v98
	v_div_fixup_f32 v16, v16, v69, 1.0
	v_pk_add_f32 v[94:95], v[18:19], v[24:25]
	v_lshlrev_b32_e32 v98, 16, v100
	v_pk_fma_f32 v[18:19], v[16:17], v[94:95], v[24:25] op_sel_hi:[0,1,1] neg_lo:[0,0,1] neg_hi:[0,0,1]
	v_pk_add_f32 v[24:25], v[26:27], v[134:135] neg_lo:[0,1] neg_hi:[0,1]
	v_lshlrev_b32_e32 v26, 16, v99
	v_and_b32_e32 v27, 0xffff0000, v99
	v_and_b32_e32 v99, 0xffff0000, v100
	v_lshlrev_b32_e32 v100, 16, v101
	v_and_b32_e32 v101, 0xffff0000, v101
	v_pk_add_f32 v[24:25], v[24:25], v[26:27]
	v_pk_add_f32 v[92:93], v[92:93], v[98:99]
	v_pk_add_f32 v[96:97], v[96:97], v[100:101]
	v_pk_fma_f32 v[26:27], v[16:17], v[24:25], v[26:27] op_sel_hi:[0,1,1] neg_lo:[0,0,1] neg_hi:[0,0,1]
	v_pk_fma_f32 v[98:99], v[16:17], v[92:93], v[98:99] op_sel_hi:[0,1,1] neg_lo:[0,0,1] neg_hi:[0,0,1]
	v_pk_fma_f32 v[100:101], v[16:17], v[96:97], v[100:101] op_sel_hi:[0,1,1] neg_lo:[0,0,1] neg_hi:[0,0,1]
	v_cvt_pk_bf16_f32 v16, v18, v19
	v_min_i32_e32 v18, 3, v117
	v_add_u32_e32 v18, 1, v18
	v_cvt_f32_i32_e32 v69, v18
	v_cvt_pk_bf16_f32 v18, v98, v99
	v_cvt_pk_bf16_f32 v17, v26, v27
	v_lshlrev_b64 v[26:27], 12, v[74:75]
	v_div_scale_f32 v98, s[46:47], v69, v69, 1.0
	v_rcp_f32_e32 v99, v98
	v_cvt_pk_bf16_f32 v19, v100, v101
	v_lshl_add_u64 v[26:27], v[62:63], 0, v[26:27]
	global_store_dwordx4 v[26:27], v[16:19], off offset:512
	v_pk_add_f32 v[24:25], v[24:25], v[126:127] neg_lo:[0,1] neg_hi:[0,1]
	s_nop 0
	v_fma_f32 v16, -v98, v99, 1.0
	v_fmac_f32_e32 v99, v16, v99
	v_div_scale_f32 v16, vcc, 1.0, v69, 1.0
	v_mul_f32_e32 v17, v16, v99
	v_fma_f32 v18, -v98, v17, v16
	v_fmac_f32_e32 v17, v18, v99
	v_fma_f32 v16, -v98, v17, v16
	v_div_fmas_f32 v16, v16, v99, v17
	v_pk_add_f32 v[18:19], v[94:95], v[90:91] neg_lo:[0,1] neg_hi:[0,1]
	s_waitcnt vmcnt(10)
	v_lshlrev_b32_e32 v90, 16, v102
	v_and_b32_e32 v91, 0xffff0000, v102
	v_div_fixup_f32 v16, v16, v69, 1.0
	v_pk_add_f32 v[94:95], v[18:19], v[90:91]
	s_nop 0
	v_pk_fma_f32 v[18:19], v[16:17], v[94:95], v[90:91] op_sel_hi:[0,1,1] neg_lo:[0,0,1] neg_hi:[0,0,1]
	v_lshlrev_b32_e32 v90, 16, v103
	v_and_b32_e32 v91, 0xffff0000, v103
	v_pk_add_f32 v[24:25], v[24:25], v[90:91]
	s_nop 0
	v_pk_fma_f32 v[98:99], v[16:17], v[24:25], v[90:91] op_sel_hi:[0,1,1] neg_lo:[0,0,1] neg_hi:[0,0,1]
	v_pk_add_f32 v[90:91], v[92:93], v[136:137] neg_lo:[0,1] neg_hi:[0,1]
	v_lshlrev_b32_e32 v92, 16, v104
	v_and_b32_e32 v93, 0xffff0000, v104
	v_pk_add_f32 v[110:111], v[90:91], v[92:93]
	v_pk_add_f32 v[90:91], v[96:97], v[148:149] neg_lo:[0,1] neg_hi:[0,1]
	v_lshlrev_b32_e32 v96, 16, v105
	v_and_b32_e32 v97, 0xffff0000, v105
	v_pk_add_f32 v[126:127], v[90:91], v[96:97]
	v_cvt_pk_bf16_f32 v90, v18, v19
	v_min_i32_e32 v18, 3, v116
	v_add_u32_e32 v18, 1, v18
	v_cvt_f32_i32_e32 v69, v18
	v_pk_fma_f32 v[92:93], v[16:17], v[110:111], v[92:93] op_sel_hi:[0,1,1] neg_lo:[0,0,1] neg_hi:[0,0,1]
	v_pk_fma_f32 v[16:17], v[16:17], v[126:127], v[96:97] op_sel_hi:[0,1,1] neg_lo:[0,0,1] neg_hi:[0,0,1]
	v_cvt_pk_bf16_f32 v92, v92, v93
	v_div_scale_f32 v96, s[46:47], v69, v69, 1.0
	v_rcp_f32_e32 v97, v96
	v_cvt_pk_bf16_f32 v93, v16, v17
	v_lshlrev_b64 v[16:17], 12, v[72:73]
	v_lshl_add_u64 v[18:19], v[62:63], 0, v[16:17]
	v_fma_f32 v16, -v96, v97, 1.0
	v_fmac_f32_e32 v97, v16, v97
	v_div_scale_f32 v16, vcc, 1.0, v69, 1.0
	v_cvt_pk_bf16_f32 v91, v98, v99
	v_mul_f32_e32 v17, v16, v97
	global_store_dwordx4 v[18:19], v[90:93], off offset:512
	v_pk_add_f32 v[24:25], v[24:25], v[128:129] neg_lo:[0,1] neg_hi:[0,1]
	v_add_u32_e32 v136, -7, v66
	v_fma_f32 v90, -v96, v17, v16
	v_fmac_f32_e32 v17, v90, v97
	v_fma_f32 v16, -v96, v17, v16
	v_div_fmas_f32 v16, v16, v97, v17
	s_waitcnt vmcnt(9)
	v_lshlrev_b32_e32 v92, 16, v56
	v_and_b32_e32 v93, 0xffff0000, v56
	v_lshlrev_b32_e32 v56, 16, v57
	v_and_b32_e32 v57, 0xffff0000, v57
	v_div_fixup_f32 v16, v16, v69, 1.0
	v_pk_add_f32 v[128:129], v[24:25], v[56:57]
	v_pk_add_f32 v[90:91], v[94:95], v[106:107] neg_lo:[0,1] neg_hi:[0,1]
	v_pk_fma_f32 v[24:25], v[16:17], v[128:129], v[56:57] op_sel_hi:[0,1,1] neg_lo:[0,0,1] neg_hi:[0,0,1]
	v_max_i32_e32 v56, s8, v136
	v_ashrrev_i32_e32 v57, 31, v56
	v_pk_add_f32 v[106:107], v[90:91], v[92:93]
	v_lshlrev_b64 v[56:57], 12, v[56:57]
	v_pk_fma_f32 v[134:135], v[16:17], v[106:107], v[92:93] op_sel_hi:[0,1,1] neg_lo:[0,0,1] neg_hi:[0,0,1]
	v_lshl_add_u64 v[56:57], v[64:65], 0, v[56:57]
	v_add_u32_e32 v17, -6, v66
	global_load_dwordx4 v[90:93], v[56:57], off offset:1024
	v_max_i32_e32 v56, s8, v17
	v_ashrrev_i32_e32 v57, 31, v56
	v_lshlrev_b64 v[56:57], 12, v[56:57]
	v_lshl_add_u64 v[56:57], v[64:65], 0, v[56:57]
	v_add_u32_e32 v17, -5, v66
	global_load_dwordx4 v[94:97], v[56:57], off offset:1024
	v_max_i32_e32 v56, s8, v17
	v_ashrrev_i32_e32 v57, 31, v56
	v_lshlrev_b64 v[56:57], 12, v[56:57]
	v_lshl_add_u64 v[56:57], v[64:65], 0, v[56:57]
	v_add_u32_e32 v17, -4, v66
	global_load_dwordx4 v[98:101], v[56:57], off offset:1024
	v_max_i32_e32 v56, s8, v17
	v_ashrrev_i32_e32 v57, 31, v56
	v_lshlrev_b64 v[56:57], 12, v[56:57]
	v_lshl_add_u64 v[56:57], v[64:65], 0, v[56:57]
	global_load_dwordx4 v[102:105], v[56:57], off offset:1024
	v_pk_add_f32 v[56:57], v[110:111], v[130:131] neg_lo:[0,1] neg_hi:[0,1]
	v_lshlrev_b32_e32 v110, 16, v58
	v_and_b32_e32 v111, 0xffff0000, v58
	v_pk_add_f32 v[130:131], v[56:57], v[110:111]
	v_pk_add_f32 v[56:57], v[126:127], v[146:147] neg_lo:[0,1] neg_hi:[0,1]
	v_lshlrev_b32_e32 v58, 16, v59
	v_and_b32_e32 v59, 0xffff0000, v59
	v_pk_add_f32 v[126:127], v[56:57], v[58:59]
	v_cvt_pk_bf16_f32 v57, v24, v25
	v_min_i32_e32 v24, 3, v60
	v_add_u32_e32 v24, 1, v24
	v_cvt_f32_i32_e32 v69, v24
	v_pk_fma_f32 v[110:111], v[16:17], v[130:131], v[110:111] op_sel_hi:[0,1,1] neg_lo:[0,0,1] neg_hi:[0,0,1]
	v_pk_fma_f32 v[16:17], v[16:17], v[126:127], v[58:59] op_sel_hi:[0,1,1] neg_lo:[0,0,1] neg_hi:[0,0,1]
	v_cvt_pk_bf16_f32 v58, v110, v111
	v_div_scale_f32 v110, s[8:9], v69, v69, 1.0
	v_rcp_f32_e32 v111, v110
	v_cvt_pk_bf16_f32 v59, v16, v17
	v_lshlrev_b64 v[16:17], 12, v[70:71]
	v_lshl_add_u64 v[24:25], v[62:63], 0, v[16:17]
	v_fma_f32 v16, -v110, v111, 1.0
	v_fmac_f32_e32 v111, v16, v111
	v_div_scale_f32 v16, vcc, 1.0, v69, 1.0
	v_cvt_pk_bf16_f32 v56, v134, v135
	v_mul_f32_e32 v17, v16, v111
	global_store_dwordx4 v[24:25], v[56:59], off offset:512
	s_nop 1
	v_fma_f32 v56, -v110, v17, v16
	v_fmac_f32_e32 v17, v56, v111
	v_fma_f32 v16, -v110, v17, v16
	v_div_fmas_f32 v16, v16, v111, v17
	v_pk_add_f32 v[56:57], v[106:107], v[108:109] neg_lo:[0,1] neg_hi:[0,1]
	s_waitcnt vmcnt(12)
	v_lshlrev_b32_e32 v58, 16, v52
	v_and_b32_e32 v59, 0xffff0000, v52
	v_div_fixup_f32 v16, v16, v69, 1.0
	v_pk_add_f32 v[56:57], v[56:57], v[58:59]
	v_lshlrev_b32_e32 v52, 16, v53
	v_pk_fma_f32 v[56:57], v[16:17], v[56:57], v[58:59] op_sel_hi:[0,1,1] neg_lo:[0,0,1] neg_hi:[0,0,1]
	v_pk_add_f32 v[58:59], v[128:129], v[132:133] neg_lo:[0,1] neg_hi:[0,1]
	v_and_b32_e32 v53, 0xffff0000, v53
	v_pk_add_f32 v[58:59], v[58:59], v[52:53]
	v_lshlrev_b32_e32 v106, 16, v54
	v_pk_fma_f32 v[58:59], v[16:17], v[58:59], v[52:53] op_sel_hi:[0,1,1] neg_lo:[0,0,1] neg_hi:[0,0,1]
	v_pk_add_f32 v[52:53], v[130:131], v[138:139] neg_lo:[0,1] neg_hi:[0,1]
	v_and_b32_e32 v107, 0xffff0000, v54
	v_pk_add_f32 v[52:53], v[52:53], v[106:107]
	v_lshlrev_b32_e32 v54, 16, v55
	v_pk_fma_f32 v[106:107], v[16:17], v[52:53], v[106:107] op_sel_hi:[0,1,1] neg_lo:[0,0,1] neg_hi:[0,0,1]
	v_pk_add_f32 v[52:53], v[126:127], v[142:143] neg_lo:[0,1] neg_hi:[0,1]
	v_and_b32_e32 v55, 0xffff0000, v55
	v_pk_add_f32 v[52:53], v[52:53], v[54:55]
	v_ashrrev_i32_e32 v69, 31, v68
	v_pk_fma_f32 v[16:17], v[16:17], v[52:53], v[54:55] op_sel_hi:[0,1,1] neg_lo:[0,0,1] neg_hi:[0,0,1]
	v_cvt_pk_bf16_f32 v55, v16, v17
	v_lshlrev_b64 v[16:17], 12, v[68:69]
	v_cvt_pk_bf16_f32 v52, v56, v57
	v_cvt_pk_bf16_f32 v53, v58, v59
	v_cvt_pk_bf16_f32 v54, v106, v107
	v_lshl_add_u64 v[16:17], v[62:63], 0, v[16:17]
	global_store_dwordx4 v[16:17], v[52:55], off offset:512
	s_nop 1
	v_add_u32_e32 v52, s10, v136
	v_cmp_lt_i32_e32 vcc, -1, v52
	s_waitcnt vmcnt(5)
	s_nop 0
	v_cndmask_b32_e32 v53, 0, v93, vcc
	v_cndmask_b32_e32 v54, 0, v92, vcc
	v_cndmask_b32_e32 v55, 0, v91, vcc
	v_cndmask_b32_e32 v56, 0, v90, vcc
	v_cmp_lt_i32_e32 vcc, -2, v52
	v_lshlrev_b32_e32 v130, 16, v56
	v_and_b32_e32 v131, 0xffff0000, v56
	s_waitcnt vmcnt(4)
	v_cndmask_b32_e32 v57, 0, v97, vcc
	v_cndmask_b32_e32 v58, 0, v96, vcc
	v_cndmask_b32_e32 v59, 0, v95, vcc
	v_cndmask_b32_e32 v69, 0, v94, vcc
	v_cmp_lt_i32_e32 vcc, -3, v52
	v_lshlrev_b32_e32 v106, 16, v69
	v_and_b32_e32 v107, 0xffff0000, v69
	s_waitcnt vmcnt(3)
	v_cndmask_b32_e32 v94, 0, v101, vcc
	v_cndmask_b32_e32 v90, 0, v100, vcc
	v_cndmask_b32_e32 v91, 0, v99, vcc
	v_cndmask_b32_e32 v92, 0, v98, vcc
	v_cmp_lt_i32_e32 vcc, -4, v52
	v_lshlrev_b32_e32 v96, 16, v92
	v_and_b32_e32 v97, 0xffff0000, v92
	s_waitcnt vmcnt(2)
	v_cndmask_b32_e32 v95, 0, v105, vcc
	v_cndmask_b32_e32 v99, 0, v104, vcc
	v_cndmask_b32_e32 v93, 0, v103, vcc
	v_cndmask_b32_e32 v98, 0, v102, vcc
	v_cmp_lt_i32_e32 vcc, -5, v52
	v_lshlrev_b32_e32 v102, 16, v59
	v_and_b32_e32 v103, 0xffff0000, v59
	v_cndmask_b32_e32 v127, 0, v51, vcc
	v_cndmask_b32_e32 v110, 0, v50, vcc
	v_cndmask_b32_e32 v49, 0, v49, vcc
	v_cndmask_b32_e32 v48, 0, v48, vcc
	v_cmp_lt_i32_e32 vcc, -6, v52
	v_lshlrev_b32_e32 v104, 16, v58
	v_and_b32_e32 v105, 0xffff0000, v58
	v_cndmask_b32_e32 v152, 0, v47, vcc
	v_cndmask_b32_e32 v111, 0, v46, vcc
	v_cndmask_b32_e32 v140, 0, v45, vcc
	v_cndmask_b32_e32 v45, 0, v44, vcc
	v_cmp_lt_i32_e32 vcc, -7, v52
	v_lshlrev_b32_e32 v58, 16, v98
	v_and_b32_e32 v59, 0xffff0000, v98
	v_cndmask_b32_e32 v46, 0, v40, vcc
	v_min_i32_e32 v40, 7, v122
	v_add_u32_e32 v40, 1, v40
	v_cvt_f32_i32_e32 v40, v40
	v_cndmask_b32_e32 v52, 0, v41, vcc
	v_cndmask_b32_e32 v146, 0, v42, vcc
	v_cndmask_b32_e32 v154, 0, v43, vcc
	v_div_scale_f32 v41, s[8:9], v40, v40, 1.0
	v_rcp_f32_e32 v42, v41
	v_lshlrev_b32_e32 v50, 16, v48
	v_and_b32_e32 v51, 0xffff0000, v48
	v_lshlrev_b32_e32 v132, 16, v55
	v_fma_f32 v43, -v41, v42, 1.0
	v_fmac_f32_e32 v42, v43, v42
	v_div_scale_f32 v43, vcc, 1.0, v40, 1.0
	v_mul_f32_e32 v44, v43, v42
	v_fma_f32 v47, -v41, v44, v43
	v_fmac_f32_e32 v44, v47, v42
	v_fma_f32 v41, -v41, v44, v43
	v_div_fmas_f32 v41, v41, v42, v44
	v_div_fixup_f32 v126, v41, v40, 1.0
	v_pk_add_f32 v[40:41], v[130:131], 0 op_sel_hi:[1,0]
	v_lshlrev_b32_e32 v44, 16, v45
	v_pk_add_f32 v[40:41], v[40:41], v[106:107]
	v_and_b32_e32 v45, 0xffff0000, v45
	v_pk_add_f32 v[40:41], v[40:41], v[96:97]
	v_and_b32_e32 v133, 0xffff0000, v55
	v_pk_add_f32 v[40:41], v[40:41], v[58:59]
	v_and_b32_e32 v47, 0xffff0000, v36
	v_pk_add_f32 v[40:41], v[40:41], v[50:51]
	v_lshlrev_b32_e32 v108, 16, v91
	v_pk_add_f32 v[42:43], v[40:41], v[44:45]
	v_lshlrev_b32_e32 v40, 16, v46
	v_and_b32_e32 v41, 0xffff0000, v46
	v_pk_add_f32 v[42:43], v[42:43], v[40:41]
	v_lshlrev_b32_e32 v46, 16, v36
	v_pk_add_f32 v[138:139], v[42:43], v[46:47]
	v_pk_add_f32 v[42:43], v[132:133], 0 op_sel_hi:[1,0]
	v_and_b32_e32 v109, 0xffff0000, v91
	v_pk_add_f32 v[42:43], v[42:43], v[102:103]
	v_lshlrev_b32_e32 v92, 16, v93
	v_pk_add_f32 v[42:43], v[42:43], v[108:109]
	v_and_b32_e32 v93, 0xffff0000, v93
	v_lshlrev_b32_e32 v134, 16, v54
	v_and_b32_e32 v135, 0xffff0000, v54
	v_pk_add_f32 v[42:43], v[42:43], v[92:93]
	v_lshlrev_b32_e32 v54, 16, v49
	v_and_b32_e32 v55, 0xffff0000, v49
	v_pk_fma_f32 v[128:129], v[126:127], v[138:139], v[46:47] op_sel_hi:[0,1,1] neg_lo:[0,0,1] neg_hi:[0,0,1]
	v_pk_add_f32 v[42:43], v[42:43], v[54:55]
	v_lshlrev_b32_e32 v46, 16, v140
	v_and_b32_e32 v47, 0xffff0000, v140
	v_pk_add_f32 v[48:49], v[42:43], v[46:47]
	v_lshlrev_b32_e32 v42, 16, v52
	v_and_b32_e32 v43, 0xffff0000, v52
	v_pk_add_f32 v[48:49], v[48:49], v[42:43]
	v_lshlrev_b32_e32 v36, 16, v37
	v_and_b32_e32 v37, 0xffff0000, v37
	v_pk_add_f32 v[140:141], v[48:49], v[36:37]
	v_lshlrev_b32_e32 v144, 16, v90
	v_pk_fma_f32 v[142:143], v[126:127], v[140:141], v[36:37] op_sel_hi:[0,1,1] neg_lo:[0,0,1] neg_hi:[0,0,1]
	v_pk_add_f32 v[36:37], v[134:135], 0 op_sel_hi:[1,0]
	v_and_b32_e32 v145, 0xffff0000, v90
	v_pk_add_f32 v[36:37], v[36:37], v[104:105]
	v_lshlrev_b32_e32 v98, 16, v99
	v_pk_add_f32 v[36:37], v[36:37], v[144:145]
	v_and_b32_e32 v99, 0xffff0000, v99
	v_pk_add_f32 v[36:37], v[36:37], v[98:99]
	v_lshlrev_b32_e32 v90, 16, v110
	v_and_b32_e32 v91, 0xffff0000, v110
	v_lshlrev_b32_e32 v136, 16, v53
	v_and_b32_e32 v137, 0xffff0000, v53
	v_pk_add_f32 v[36:37], v[36:37], v[90:91]
	v_lshlrev_b32_e32 v52, 16, v111
	v_and_b32_e32 v53, 0xffff0000, v111
	v_pk_add_f32 v[48:49], v[36:37], v[52:53]
	v_lshlrev_b32_e32 v36, 16, v146
	v_and_b32_e32 v37, 0xffff0000, v146
	v_lshlrev_b32_e32 v100, 16, v57
	v_and_b32_e32 v101, 0xffff0000, v57
	v_pk_add_f32 v[48:49], v[48:49], v[36:37]
	v_lshlrev_b32_e32 v56, 16, v38
	v_and_b32_e32 v57, 0xffff0000, v38
	v_pk_add_f32 v[146:147], v[48:49], v[56:57]
	v_pk_add_f32 v[48:49], v[136:137], 0 op_sel_hi:[1,0]
	v_lshlrev_b32_e32 v150, 16, v94
	v_pk_add_f32 v[48:49], v[48:49], v[100:101]
	v_and_b32_e32 v151, 0xffff0000, v94
	v_pk_add_f32 v[48:49], v[48:49], v[150:151]
	v_lshlrev_b32_e32 v110, 16, v95
	v_and_b32_e32 v111, 0xffff0000, v95
	v_min_i32_e32 v69, 7, v121
	v_pk_add_f32 v[48:49], v[48:49], v[110:111]
	v_lshlrev_b32_e32 v94, 16, v127
	v_and_b32_e32 v95, 0xffff0000, v127
	v_add_u32_e32 v69, 1, v69
	v_pk_fma_f32 v[148:149], v[126:127], v[146:147], v[56:57] op_sel_hi:[0,1,1] neg_lo:[0,0,1] neg_hi:[0,0,1]
	v_pk_add_f32 v[48:49], v[48:49], v[94:95]
	v_lshlrev_b32_e32 v56, 16, v152
	v_and_b32_e32 v57, 0xffff0000, v152
	v_cvt_f32_i32_e32 v69, v69
	v_pk_add_f32 v[152:153], v[48:49], v[56:57]
	v_lshlrev_b32_e32 v48, 16, v154
	v_and_b32_e32 v49, 0xffff0000, v154
	v_pk_add_f32 v[152:153], v[152:153], v[48:49]
	v_lshlrev_b32_e32 v38, 16, v39
	v_and_b32_e32 v39, 0xffff0000, v39
	v_pk_add_f32 v[152:153], v[152:153], v[38:39]
	s_nop 0
	v_pk_fma_f32 v[38:39], v[126:127], v[152:153], v[38:39] op_sel_hi:[0,1,1] neg_lo:[0,0,1] neg_hi:[0,0,1]
	v_cvt_pk_bf16_f32 v127, v142, v143
	v_div_scale_f32 v142, s[8:9], v69, v69, 1.0
	v_rcp_f32_e32 v143, v142
	v_cvt_pk_bf16_f32 v126, v128, v129
	v_cvt_pk_bf16_f32 v129, v38, v39
	v_cvt_pk_bf16_f32 v128, v148, v149
	v_fma_f32 v38, -v142, v143, 1.0
	v_fmac_f32_e32 v143, v38, v143
	v_div_scale_f32 v38, vcc, 1.0, v69, 1.0
	v_mul_f32_e32 v39, v38, v143
	global_store_dwordx4 v[88:89], v[126:129], off offset:1024
	v_fma_f32 v88, -v142, v39, v38
	v_fmac_f32_e32 v39, v88, v143
	v_fma_f32 v38, -v142, v39, v38
	v_div_fmas_f32 v38, v38, v143, v39
	v_lshlrev_b32_e32 v126, 16, v32
	v_and_b32_e32 v127, 0xffff0000, v32
	v_pk_add_f32 v[128:129], v[140:141], v[132:133] neg_lo:[0,1] neg_hi:[0,1]
	v_lshlrev_b32_e32 v32, 16, v33
	v_and_b32_e32 v33, 0xffff0000, v33
	v_div_fixup_f32 v38, v38, v69, 1.0
	v_pk_add_f32 v[128:129], v[128:129], v[32:33]
	v_pk_add_f32 v[88:89], v[138:139], v[130:131] neg_lo:[0,1] neg_hi:[0,1]
	v_pk_fma_f32 v[130:131], v[38:39], v[128:129], v[32:33] op_sel_hi:[0,1,1] neg_lo:[0,0,1] neg_hi:[0,0,1]
	v_pk_add_f32 v[32:33], v[146:147], v[134:135] neg_lo:[0,1] neg_hi:[0,1]
	v_lshlrev_b32_e32 v132, 16, v34
	v_and_b32_e32 v133, 0xffff0000, v34
	v_pk_add_f32 v[134:135], v[32:33], v[132:133]
	v_pk_add_f32 v[32:33], v[152:153], v[136:137] neg_lo:[0,1] neg_hi:[0,1]
	v_lshlrev_b32_e32 v34, 16, v35
	v_and_b32_e32 v35, 0xffff0000, v35
	v_pk_add_f32 v[136:137], v[32:33], v[34:35]
	v_min_i32_e32 v32, 7, v120
	v_add_u32_e32 v32, 1, v32
	v_cvt_f32_i32_e32 v69, v32
	v_pk_add_f32 v[88:89], v[88:89], v[126:127]
	v_pk_fma_f32 v[132:133], v[38:39], v[134:135], v[132:133] op_sel_hi:[0,1,1] neg_lo:[0,0,1] neg_hi:[0,0,1]
	v_pk_fma_f32 v[126:127], v[38:39], v[88:89], v[126:127] op_sel_hi:[0,1,1] neg_lo:[0,0,1] neg_hi:[0,0,1]
	v_cvt_pk_bf16_f32 v32, v126, v127
	v_div_scale_f32 v126, s[8:9], v69, v69, 1.0
	v_rcp_f32_e32 v127, v126
	v_pk_fma_f32 v[38:39], v[38:39], v[136:137], v[34:35] op_sel_hi:[0,1,1] neg_lo:[0,0,1] neg_hi:[0,0,1]
	v_cvt_pk_bf16_f32 v33, v130, v131
	v_cvt_pk_bf16_f32 v34, v132, v133
	v_cvt_pk_bf16_f32 v35, v38, v39
	global_store_dwordx4 v[86:87], v[32:35], off offset:1024
	v_lshlrev_b32_e32 v38, 16, v28
	v_and_b32_e32 v39, 0xffff0000, v28
	v_fma_f32 v32, -v126, v127, 1.0
	v_fmac_f32_e32 v127, v32, v127
	v_div_scale_f32 v32, vcc, 1.0, v69, 1.0
	v_mul_f32_e32 v33, v32, v127
	v_fma_f32 v34, -v126, v33, v32
	v_fmac_f32_e32 v33, v34, v127
	v_fma_f32 v32, -v126, v33, v32
	v_div_fmas_f32 v32, v32, v127, v33
	v_pk_add_f32 v[86:87], v[128:129], v[102:103] neg_lo:[0,1] neg_hi:[0,1]
	v_lshlrev_b32_e32 v28, 16, v29
	v_and_b32_e32 v29, 0xffff0000, v29
	v_div_fixup_f32 v32, v32, v69, 1.0
	v_pk_add_f32 v[86:87], v[86:87], v[28:29]
	v_pk_add_f32 v[34:35], v[88:89], v[106:107] neg_lo:[0,1] neg_hi:[0,1]
	v_pk_fma_f32 v[88:89], v[32:33], v[86:87], v[28:29] op_sel_hi:[0,1,1] neg_lo:[0,0,1] neg_hi:[0,0,1]
	v_pk_add_f32 v[28:29], v[134:135], v[104:105] neg_lo:[0,1] neg_hi:[0,1]
	v_lshlrev_b32_e32 v102, 16, v30
	v_and_b32_e32 v103, 0xffff0000, v30
	v_pk_add_f32 v[104:105], v[28:29], v[102:103]
	v_pk_add_f32 v[28:29], v[136:137], v[100:101] neg_lo:[0,1] neg_hi:[0,1]
	v_lshlrev_b32_e32 v30, 16, v31
	v_and_b32_e32 v31, 0xffff0000, v31
	v_pk_add_f32 v[100:101], v[28:29], v[30:31]
	v_min_i32_e32 v28, 7, v119
	v_add_u32_e32 v28, 1, v28
	v_cvt_f32_i32_e32 v69, v28
	v_pk_add_f32 v[34:35], v[34:35], v[38:39]
	v_pk_fma_f32 v[102:103], v[32:33], v[104:105], v[102:103] op_sel_hi:[0,1,1] neg_lo:[0,0,1] neg_hi:[0,0,1]
	v_pk_fma_f32 v[38:39], v[32:33], v[34:35], v[38:39] op_sel_hi:[0,1,1] neg_lo:[0,0,1] neg_hi:[0,0,1]
	v_cvt_pk_bf16_f32 v28, v38, v39
	v_div_scale_f32 v38, s[8:9], v69, v69, 1.0
	v_rcp_f32_e32 v39, v38
	v_pk_fma_f32 v[32:33], v[32:33], v[100:101], v[30:31] op_sel_hi:[0,1,1] neg_lo:[0,0,1] neg_hi:[0,0,1]
	v_cvt_pk_bf16_f32 v29, v88, v89
	v_cvt_pk_bf16_f32 v30, v102, v103
	v_cvt_pk_bf16_f32 v31, v32, v33
	global_store_dwordx4 v[84:85], v[28:31], off offset:1024
	v_lshlrev_b32_e32 v32, 16, v20
	v_and_b32_e32 v33, 0xffff0000, v20
	v_fma_f32 v28, -v38, v39, 1.0
	v_fmac_f32_e32 v39, v28, v39
	v_div_scale_f32 v28, vcc, 1.0, v69, 1.0
	v_mul_f32_e32 v29, v28, v39
	v_fma_f32 v30, -v38, v29, v28
	v_fmac_f32_e32 v29, v30, v39
	v_fma_f32 v28, -v38, v29, v28
	v_div_fmas_f32 v28, v28, v39, v29
	v_pk_add_f32 v[30:31], v[34:35], v[96:97] neg_lo:[0,1] neg_hi:[0,1]
	v_pk_add_f32 v[34:35], v[86:87], v[108:109] neg_lo:[0,1] neg_hi:[0,1]
	v_lshlrev_b32_e32 v20, 16, v21
	v_and_b32_e32 v21, 0xffff0000, v21
	v_div_fixup_f32 v28, v28, v69, 1.0
	v_pk_add_f32 v[34:35], v[34:35], v[20:21]
	v_lshlrev_b32_e32 v84, 16, v22
	v_pk_fma_f32 v[38:39], v[28:29], v[34:35], v[20:21] op_sel_hi:[0,1,1] neg_lo:[0,0,1] neg_hi:[0,0,1]
	v_pk_add_f32 v[20:21], v[104:105], v[144:145] neg_lo:[0,1] neg_hi:[0,1]
	v_and_b32_e32 v85, 0xffff0000, v22
	v_pk_add_f32 v[86:87], v[20:21], v[84:85]
	v_pk_add_f32 v[20:21], v[100:101], v[150:151] neg_lo:[0,1] neg_hi:[0,1]
	v_lshlrev_b32_e32 v22, 16, v23
	v_and_b32_e32 v23, 0xffff0000, v23
	v_pk_add_f32 v[88:89], v[20:21], v[22:23]
	v_min_i32_e32 v20, 7, v118
	v_add_u32_e32 v20, 1, v20
	v_cvt_f32_i32_e32 v69, v20
	v_pk_add_f32 v[30:31], v[30:31], v[32:33]
	v_pk_fma_f32 v[84:85], v[28:29], v[86:87], v[84:85] op_sel_hi:[0,1,1] neg_lo:[0,0,1] neg_hi:[0,0,1]
	v_pk_fma_f32 v[32:33], v[28:29], v[30:31], v[32:33] op_sel_hi:[0,1,1] neg_lo:[0,0,1] neg_hi:[0,0,1]
	v_cvt_pk_bf16_f32 v20, v32, v33
	v_div_scale_f32 v32, s[8:9], v69, v69, 1.0
	v_rcp_f32_e32 v33, v32
	v_pk_fma_f32 v[28:29], v[28:29], v[88:89], v[22:23] op_sel_hi:[0,1,1] neg_lo:[0,0,1] neg_hi:[0,0,1]
	v_cvt_pk_bf16_f32 v21, v38, v39
	v_cvt_pk_bf16_f32 v22, v84, v85
	v_cvt_pk_bf16_f32 v23, v28, v29
	global_store_dwordx4 v[82:83], v[20:23], off offset:1024
	v_lshlrev_b32_e32 v28, 16, v12
	v_and_b32_e32 v29, 0xffff0000, v12
	v_fma_f32 v20, -v32, v33, 1.0
	v_fmac_f32_e32 v33, v20, v33
	v_div_scale_f32 v20, vcc, 1.0, v69, 1.0
	v_mul_f32_e32 v21, v20, v33
	v_fma_f32 v22, -v32, v21, v20
	v_fmac_f32_e32 v21, v22, v33
	v_fma_f32 v20, -v32, v21, v20
	v_div_fmas_f32 v20, v20, v33, v21
	v_pk_add_f32 v[22:23], v[30:31], v[58:59] neg_lo:[0,1] neg_hi:[0,1]
	v_pk_add_f32 v[30:31], v[34:35], v[92:93] neg_lo:[0,1] neg_hi:[0,1]
	v_lshlrev_b32_e32 v12, 16, v13
	v_and_b32_e32 v13, 0xffff0000, v13
	v_div_fixup_f32 v20, v20, v69, 1.0
	v_pk_add_f32 v[30:31], v[30:31], v[12:13]
	v_lshlrev_b32_e32 v34, 16, v14
	v_pk_fma_f32 v[32:33], v[20:21], v[30:31], v[12:13] op_sel_hi:[0,1,1] neg_lo:[0,0,1] neg_hi:[0,0,1]
	v_pk_add_f32 v[12:13], v[86:87], v[98:99] neg_lo:[0,1] neg_hi:[0,1]
	v_and_b32_e32 v35, 0xffff0000, v14
	v_pk_add_f32 v[38:39], v[12:13], v[34:35]
	v_pk_add_f32 v[12:13], v[88:89], v[110:111] neg_lo:[0,1] neg_hi:[0,1]
	v_lshlrev_b32_e32 v14, 16, v15
	v_and_b32_e32 v15, 0xffff0000, v15
	v_pk_add_f32 v[58:59], v[12:13], v[14:15]
	v_min_i32_e32 v12, 7, v117
	v_add_u32_e32 v12, 1, v12
	v_cvt_f32_i32_e32 v69, v12
	v_pk_add_f32 v[22:23], v[22:23], v[28:29]
	v_pk_fma_f32 v[34:35], v[20:21], v[38:39], v[34:35] op_sel_hi:[0,1,1] neg_lo:[0,0,1] neg_hi:[0,0,1]
	v_pk_fma_f32 v[28:29], v[20:21], v[22:23], v[28:29] op_sel_hi:[0,1,1] neg_lo:[0,0,1] neg_hi:[0,0,1]
	v_cvt_pk_bf16_f32 v12, v28, v29
	v_div_scale_f32 v28, s[8:9], v69, v69, 1.0
	v_rcp_f32_e32 v29, v28
	v_pk_fma_f32 v[20:21], v[20:21], v[58:59], v[14:15] op_sel_hi:[0,1,1] neg_lo:[0,0,1] neg_hi:[0,0,1]
	v_cvt_pk_bf16_f32 v13, v32, v33
	v_cvt_pk_bf16_f32 v14, v34, v35
	v_cvt_pk_bf16_f32 v15, v20, v21
	global_store_dwordx4 v[26:27], v[12:15], off offset:1024
	v_lshlrev_b32_e32 v20, 16, v8
	v_and_b32_e32 v21, 0xffff0000, v8
	v_fma_f32 v12, -v28, v29, 1.0
	v_fmac_f32_e32 v29, v12, v29
	v_div_scale_f32 v12, vcc, 1.0, v69, 1.0
	v_mul_f32_e32 v13, v12, v29
	v_fma_f32 v14, -v28, v13, v12
	v_fmac_f32_e32 v13, v14, v29
	v_fma_f32 v12, -v28, v13, v12
	v_div_fmas_f32 v12, v12, v29, v13
	v_pk_add_f32 v[14:15], v[22:23], v[50:51] neg_lo:[0,1] neg_hi:[0,1]
	v_pk_add_f32 v[22:23], v[30:31], v[54:55] neg_lo:[0,1] neg_hi:[0,1]
	v_lshlrev_b32_e32 v8, 16, v9
	v_and_b32_e32 v9, 0xffff0000, v9
	v_div_fixup_f32 v12, v12, v69, 1.0
	v_pk_add_f32 v[22:23], v[22:23], v[8:9]
	v_lshlrev_b32_e32 v28, 16, v10
	v_pk_fma_f32 v[26:27], v[12:13], v[22:23], v[8:9] op_sel_hi:[0,1,1] neg_lo:[0,0,1] neg_hi:[0,0,1]
	v_pk_add_f32 v[8:9], v[38:39], v[90:91] neg_lo:[0,1] neg_hi:[0,1]
	v_and_b32_e32 v29, 0xffff0000, v10
	v_pk_add_f32 v[30:31], v[8:9], v[28:29]
	v_pk_add_f32 v[8:9], v[58:59], v[94:95] neg_lo:[0,1] neg_hi:[0,1]
	v_lshlrev_b32_e32 v10, 16, v11
	v_and_b32_e32 v11, 0xffff0000, v11
	v_pk_add_f32 v[32:33], v[8:9], v[10:11]
	v_min_i32_e32 v8, 7, v116
	v_add_u32_e32 v8, 1, v8
	v_cvt_f32_i32_e32 v34, v8
	v_pk_add_f32 v[14:15], v[14:15], v[20:21]
	v_pk_fma_f32 v[28:29], v[12:13], v[30:31], v[28:29] op_sel_hi:[0,1,1] neg_lo:[0,0,1] neg_hi:[0,0,1]
	v_pk_fma_f32 v[20:21], v[12:13], v[14:15], v[20:21] op_sel_hi:[0,1,1] neg_lo:[0,0,1] neg_hi:[0,0,1]
	v_cvt_pk_bf16_f32 v8, v20, v21
	v_div_scale_f32 v20, s[8:9], v34, v34, 1.0
	v_rcp_f32_e32 v21, v20
	v_pk_fma_f32 v[12:13], v[12:13], v[32:33], v[10:11] op_sel_hi:[0,1,1] neg_lo:[0,0,1] neg_hi:[0,0,1]
	v_cvt_pk_bf16_f32 v9, v26, v27
	v_cvt_pk_bf16_f32 v10, v28, v29
	v_cvt_pk_bf16_f32 v11, v12, v13
	global_store_dwordx4 v[18:19], v[8:11], off offset:1024
	v_lshlrev_b32_e32 v12, 16, v4
	v_and_b32_e32 v13, 0xffff0000, v4
	v_fma_f32 v8, -v20, v21, 1.0
	v_fmac_f32_e32 v21, v8, v21
	v_div_scale_f32 v8, vcc, 1.0, v34, 1.0
	v_mul_f32_e32 v9, v8, v21
	v_fma_f32 v10, -v20, v9, v8
	v_fmac_f32_e32 v9, v10, v21
	v_fma_f32 v8, -v20, v9, v8
	v_div_fmas_f32 v8, v8, v21, v9
	v_pk_add_f32 v[10:11], v[14:15], v[44:45] neg_lo:[0,1] neg_hi:[0,1]
	v_pk_add_f32 v[14:15], v[22:23], v[46:47] neg_lo:[0,1] neg_hi:[0,1]
	v_lshlrev_b32_e32 v4, 16, v5
	v_and_b32_e32 v5, 0xffff0000, v5
	v_div_fixup_f32 v8, v8, v34, 1.0
	v_pk_add_f32 v[14:15], v[14:15], v[4:5]
	v_lshlrev_b32_e32 v20, 16, v6
	v_pk_fma_f32 v[18:19], v[8:9], v[14:15], v[4:5] op_sel_hi:[0,1,1] neg_lo:[0,0,1] neg_hi:[0,0,1]
	v_pk_add_f32 v[4:5], v[30:31], v[52:53] neg_lo:[0,1] neg_hi:[0,1]
	v_and_b32_e32 v21, 0xffff0000, v6
	v_pk_add_f32 v[22:23], v[4:5], v[20:21]
	v_pk_add_f32 v[4:5], v[32:33], v[56:57] neg_lo:[0,1] neg_hi:[0,1]
	v_lshlrev_b32_e32 v6, 16, v7
	v_and_b32_e32 v7, 0xffff0000, v7
	v_pk_add_f32 v[26:27], v[4:5], v[6:7]
	v_min_i32_e32 v4, 7, v60
	v_add_u32_e32 v4, 1, v4
	v_cvt_f32_i32_e32 v28, v4
	v_pk_add_f32 v[10:11], v[10:11], v[12:13]
	v_pk_fma_f32 v[20:21], v[8:9], v[22:23], v[20:21] op_sel_hi:[0,1,1] neg_lo:[0,0,1] neg_hi:[0,0,1]
	v_pk_fma_f32 v[12:13], v[8:9], v[10:11], v[12:13] op_sel_hi:[0,1,1] neg_lo:[0,0,1] neg_hi:[0,0,1]
	v_cvt_pk_bf16_f32 v4, v12, v13
	v_div_scale_f32 v12, s[8:9], v28, v28, 1.0
	v_rcp_f32_e32 v13, v12
	v_pk_fma_f32 v[8:9], v[8:9], v[26:27], v[6:7] op_sel_hi:[0,1,1] neg_lo:[0,0,1] neg_hi:[0,0,1]
	v_cvt_pk_bf16_f32 v5, v18, v19
	v_cvt_pk_bf16_f32 v6, v20, v21
	v_cvt_pk_bf16_f32 v7, v8, v9
	global_store_dwordx4 v[24:25], v[4:7], off offset:1024
	v_lshlrev_b32_e32 v8, 16, v0
	v_and_b32_e32 v9, 0xffff0000, v0
	v_fma_f32 v4, -v12, v13, 1.0
	v_fmac_f32_e32 v13, v4, v13
	v_div_scale_f32 v4, vcc, 1.0, v28, 1.0
	v_mul_f32_e32 v5, v4, v13
	v_fma_f32 v6, -v12, v5, v4
	v_fmac_f32_e32 v5, v6, v13
	v_fma_f32 v4, -v12, v5, v4
	v_div_fmas_f32 v4, v4, v13, v5
	v_pk_add_f32 v[6:7], v[10:11], v[40:41] neg_lo:[0,1] neg_hi:[0,1]
	v_div_fixup_f32 v4, v4, v28, 1.0
	v_pk_add_f32 v[6:7], v[6:7], v[8:9]
	v_lshlrev_b32_e32 v0, 16, v1
	v_pk_fma_f32 v[6:7], v[4:5], v[6:7], v[8:9] op_sel_hi:[0,1,1] neg_lo:[0,0,1] neg_hi:[0,0,1]
	v_pk_add_f32 v[8:9], v[14:15], v[42:43] neg_lo:[0,1] neg_hi:[0,1]
	v_and_b32_e32 v1, 0xffff0000, v1
	v_pk_add_f32 v[8:9], v[8:9], v[0:1]
	v_lshlrev_b32_e32 v10, 16, v2
	v_pk_fma_f32 v[8:9], v[4:5], v[8:9], v[0:1] op_sel_hi:[0,1,1] neg_lo:[0,0,1] neg_hi:[0,0,1]
	v_pk_add_f32 v[0:1], v[22:23], v[36:37] neg_lo:[0,1] neg_hi:[0,1]
	v_and_b32_e32 v11, 0xffff0000, v2
	v_pk_add_f32 v[0:1], v[0:1], v[10:11]
	v_lshlrev_b32_e32 v2, 16, v3
	v_pk_fma_f32 v[10:11], v[4:5], v[0:1], v[10:11] op_sel_hi:[0,1,1] neg_lo:[0,0,1] neg_hi:[0,0,1]
	v_pk_add_f32 v[0:1], v[26:27], v[48:49] neg_lo:[0,1] neg_hi:[0,1]
	v_and_b32_e32 v3, 0xffff0000, v3
	v_pk_add_f32 v[0:1], v[0:1], v[2:3]
	s_nop 0
	v_pk_fma_f32 v[4:5], v[4:5], v[0:1], v[2:3] op_sel_hi:[0,1,1] neg_lo:[0,0,1] neg_hi:[0,0,1]
	v_cvt_pk_bf16_f32 v0, v6, v7
	v_cvt_pk_bf16_f32 v1, v8, v9
	v_cvt_pk_bf16_f32 v2, v10, v11
	v_cvt_pk_bf16_f32 v3, v4, v5
	global_store_dwordx4 v[16:17], v[0:3], off offset:1024
	s_cbranch_execnz .LBB0_386
	s_branch .LBB0_400
